# v31: v30 + sb_attn partner-product select on the lane-half mask s[68:69] instead of v_cmp_eq + vcc select (19 VALU fewer; same values)
# speedup vs baseline: 1.0003x; 1.0003x over previous
; #define LAS __attribute__((address_space(3)))
; __device__ __forceinline__ void sb_attn(Frame& F) {
;     ...
;         { const bf16* Qp = PROJ + (tok0 + 32 * qL + r32) * NPROJ + C_SQ + 64 * h + 8 * hi;
;           bf16x8 qt[8];
; #pragma unroll
;           for (int ds = 0; ds < 4; ++ds) { qt[ds] = *(const bf16x8*)(Qp + 16 * ds); qt[4 + ds] = *(const bf16x8*)(Qp + (size_t)32 * NPROJ + 16 * ds); }
; #pragma unroll
;           for (int i = 0; i < 8; ++i) *(LAS bf16x8*)(Qs + (i * 64 + lane) * 16) = qt[i]; }
;         f32x16 oL[2], oU[2];
; #pragma unroll
;         for (int x = 0; x < 2; ++x)
; #pragma unroll
;             for (int r = 0; r < 16; ++r) { oL[x][r] = 0.f; oU[x][r] = 0.f; }
;         float CL = 1.0f, CU = 1.0f;
;         bool doneL = false, doneU = false;
;         bf16x8 kf[4]; u32x4 vreg[4];
;         { const bf16* Kp = PROJ + (tok0 + 32 * qU + r32) * NPROJ + C_SK + 64 * h + 8 * hi;
; #pragma unroll
;           for (int ds = 0; ds < 4; ++ds) kf[ds] = *(const bf16x8*)(Kp + 16 * ds);
; #pragma unroll
;           for (int n = 0; n < 4; ++n) { const int idx = lane + 64 * n; vreg[n] = *(const u32x4*)(PROJ + (tok0 + 32 * qU + (idx >> 3)) * NPROJ + C_SV + 64 * h + 8 * (idx & 7)); } }
;         auto scores = [&](int up) __attribute__((always_inline)) -> f32x16 {
;             f32x16 s;
; #pragma unroll
;             for (int r = 0; r < 16; ++r) s[r] = 0.f;
; #pragma unroll
;             for (int ds = 0; ds < 4; ++ds) { const bf16x8 qf = *(const LAS bf16x8*)(Qs + ((4 * up + ds) * 64 + lane) * 16); s = __builtin_amdgcn_mfma_f32_32x32x16_bf16(kf[ds], qf, s, 0, 0, 0); }
;     ...
;             const bool actU = !doneU, actL = (kb <= qL) && !doneL;
; #pragma unroll
;             for (int n = 0; n < 4; ++n) { const int idx = lane + 64 * n; *(LAS u32x4*)(Vb + (idx >> 3) * P64 + (idx & 7) * 16) = vreg[n]; }
;             if (actU) { const f32x16 sU = scores(1); weigh(sU, oU, CU, kb == qU); doneU = __all(CU < 0x1p-120f); }
.LBB0_305:
	s_lshl_b32 s11, s2, 1
	s_ashr_i32 s10, s2, 9
	s_and_b32 s27, s11, 0x7e
	s_ashr_i32 s11, s10, 31
	s_lshl_b32 s24, s27, 5
	s_lshl_b64 s[10:11], s[10:11], 12
	v_or_b32_e32 v2, s24, v204
	v_or_b32_e32 v218, s10, v2
	v_mov_b64_e32 v[18:19], s[8:9]
	s_and_b32 s16, s2, 0x1c0
	v_mad_u64_u32 v[2:3], s[12:13], v218, s81, v[18:19]
	v_mad_i32_i24 v3, s11, v225, v3
	s_lshl_b32 s16, s16, 1
	v_lshl_add_u64 v[2:3], v[2:3], 0, s[16:17]
	v_lshl_add_u64 v[6:7], v[2:3], 0, v[66:67]
	s_mov_b64 s[12:13], 0x1000
	v_add_co_u32_e32 v2, vcc, s35, v6
	v_lshl_add_u64 v[28:29], v[6:7], 0, s[12:13]
	s_nop 0
	v_addc_co_u32_e32 v3, vcc, 0, v7, vcc
	s_mov_b32 s12, 0x39000
	v_add_co_u32_e32 v32, vcc, s12, v6
	global_load_dwordx4 v[2:5], v[2:3], off
	s_nop 0
	v_addc_co_u32_e32 v33, vcc, 0, v7, vcc
	global_load_dwordx4 v[6:9], v[32:33], off
	global_load_dwordx4 v[10:13], v[28:29], off offset:32
	global_load_dwordx4 v[14:17], v[32:33], off offset:32
	global_load_dwordx4 v[20:23], v[28:29], off offset:64
	global_load_dwordx4 v[24:27], v[32:33], off offset:64
	s_nop 0
	global_load_dwordx4 v[28:31], v[28:29], off offset:96
	s_nop 0
	global_load_dwordx4 v[32:35], v[32:33], off offset:96
	s_or_b32 s12, s24, s10
	v_add_u32_e32 v211, s6, v205
	s_or_b32 s13, s12, 32
	s_mov_b64 s[30:31], 0x1400
	v_mov_b32_e32 v215, v67
	s_mov_b64 s[70:71], s[72:73]
	s_mov_b32 s25, 0x3800000
	v_mov_b32_e32 v219, s11
	s_mov_b64 s[74:75], 0x1400
	s_waitcnt vmcnt(7)
	ds_write_b128 v211, v[2:5]
	s_waitcnt vmcnt(5)
	ds_write_b128 v211, v[10:13] offset:1024
	s_waitcnt vmcnt(3)
	ds_write_b128 v211, v[20:23] offset:2048
	s_waitcnt vmcnt(1)
	ds_write_b128 v211, v[28:31] offset:3072
	ds_write_b128 v211, v[6:9] offset:4096
	ds_write_b128 v211, v[14:17] offset:5120
	ds_write_b128 v211, v[24:27] offset:6144
	s_waitcnt vmcnt(0)
	ds_write_b128 v211, v[32:35] offset:7168
	v_or_b32_e32 v2, s13, v204
	v_mad_u64_u32 v[2:3], s[28:29], v2, s81, v[18:19]
	v_mad_i32_i24 v3, s11, v225, v3
	v_lshl_add_u64 v[2:3], v[2:3], 0, s[16:17]
	v_lshl_add_u64 v[2:3], v[2:3], 0, v[66:67]
	v_lshl_add_u64 v[6:7], v[2:3], 0, s[30:31]
	v_add_co_u32_e32 v2, vcc, s35, v2
	v_or_b32_e32 v10, s13, v210
	s_nop 0
	v_addc_co_u32_e32 v3, vcc, 0, v3, vcc
	global_load_dwordx4 v[2:5], v[2:3], off offset:1024
	s_nop 0
	global_load_dwordx4 v[20:23], v[6:7], off offset:32
	global_load_dwordx4 v[24:27], v[6:7], off offset:64
	global_load_dwordx4 v[28:31], v[6:7], off offset:96
	v_or_b32_e32 v6, s13, v212
	v_mad_u64_u32 v[6:7], s[28:29], v6, s81, v[18:19]
	v_mad_i32_i24 v7, s11, v225, v7
	v_lshl_add_u64 v[6:7], v[6:7], 0, s[16:17]
	v_mad_u64_u32 v[10:11], s[28:29], v10, s81, v[18:19]
	v_lshl_add_u64 v[6:7], v[6:7], 0, v[214:215]
	v_mad_i32_i24 v11, s11, v225, v11
	v_or_b32_e32 v14, s13, v208
	v_add_co_u32_e32 v6, vcc, s35, v6
	v_lshl_add_u64 v[10:11], v[10:11], 0, s[16:17]
	v_mad_u64_u32 v[14:15], s[28:29], v14, s81, v[18:19]
	v_addc_co_u32_e32 v7, vcc, 0, v7, vcc
	v_lshl_add_u64 v[10:11], v[10:11], 0, v[214:215]
	v_mad_i32_i24 v15, s11, v225, v15
	v_or_b32_e32 v32, s13, v206
	v_add_co_u32_e32 v10, vcc, s35, v10
	v_lshl_add_u64 v[14:15], v[14:15], 0, s[16:17]
	v_mad_u64_u32 v[32:33], s[28:29], v32, s81, v[18:19]
	v_addc_co_u32_e32 v11, vcc, 0, v11, vcc
	v_lshl_add_u64 v[14:15], v[14:15], 0, v[214:215]
	v_mad_i32_i24 v33, s11, v225, v33
	v_add_co_u32_e32 v14, vcc, s35, v14
	v_lshl_add_u64 v[32:33], v[32:33], 0, s[16:17]
	s_nop 0
	v_addc_co_u32_e32 v15, vcc, 0, v15, vcc
	v_lshl_add_u64 v[32:33], v[32:33], 0, v[214:215]
	v_add_co_u32_e32 v32, vcc, s35, v32
	global_load_dwordx4 v[14:17], v[14:15], off offset:2048
	s_nop 0
	v_addc_co_u32_e32 v33, vcc, 0, v33, vcc
	global_load_dwordx4 v[32:35], v[32:33], off offset:2048
	s_nop 0
	global_load_dwordx4 v[6:9], v[6:7], off offset:2048
	s_nop 0
	global_load_dwordx4 v[10:13], v[10:11], off offset:2048
	s_waitcnt vmcnt(2)
	ds_write_b128 v207, v[32:35] offset:40960
	ds_write_b128 v207, v[14:17] offset:42112
	s_waitcnt vmcnt(0)
	ds_write_b128 v207, v[10:13] offset:43264
	ds_write_b128 v207, v[6:9] offset:44416
	ds_read_b128 v[6:9], v211 offset:4096
	ds_read_b128 v[32:35], v211 offset:5120
	s_waitcnt lgkmcnt(1)
	v_mfma_f32_32x32x16_bf16 v[2:17], v[2:5], v[6:9], 0
	s_waitcnt lgkmcnt(0)
	v_mfma_f32_32x32x16_bf16 v[2:17], v[20:23], v[32:35], v[2:17]
	ds_read_b128 v[20:23], v211 offset:6144
	s_waitcnt lgkmcnt(0)
	v_mfma_f32_32x32x16_bf16 v[2:17], v[24:27], v[20:23], v[2:17]
	ds_read_b128 v[20:23], v211 offset:7168
	s_waitcnt lgkmcnt(0)
; __device__ __forceinline__ void sb_attn(Frame& F) {
;     ...
;         auto weigh = [&](f32x16 s, f32x16 (&o)[2], float& C, bool diag) __attribute__((always_inline)) {
;             if (diag) {
; #pragma unroll
;                 for (int r = 0; r < 16; ++r) { const int key = (r & 3) + 8 * (r >> 2) + 4 * hi; s[r] = (key < r32) ? s[r] : -1e30f; }
;             }
;             float rm[16], bt[16];
; #pragma unroll
;             for (int r = 0; r < 16; ++r) {
;                 const float q1 = fast_rcp(1.0f + __builtin_amdgcn_exp2f(s[r]));
;                 rm[r] = q1;
;                 bt[r] = 1.0f - q1;
;             }
;             float Gs[4], Gp[4];
; #pragma unroll
;             for (int g4 = 0; g4 < 4; ++g4) { Gs[g4] = (rm[4 * g4] * rm[4 * g4 + 1]) * (rm[4 * g4 + 2] * rm[4 * g4 + 3]);
;                 const unsigned own = __builtin_bit_cast(unsigned, Gs[g4]);
;                 const u32x2 sw = __builtin_amdgcn_permlane32_swap(own, own, false, false);
;                 const unsigned r0 = sw.x, r1 = sw.y;
;                 Gp[g4] = __builtin_bit_cast(float, (r0 == own) ? r1 : r0); }
;             float run = C;
;             float a[16];
; #pragma unroll
;     ...
;                 float sfx = run * (hi == 0 ? Gp[g4] : 1.0f);
;                 a[4 * g4 + 3] = bt[4 * g4 + 3] * sfx; sfx *= rm[4 * g4 + 3];
;                 a[4 * g4 + 2] = bt[4 * g4 + 2] * sfx; sfx *= rm[4 * g4 + 2];
;                 a[4 * g4 + 1] = bt[4 * g4 + 1] * sfx; sfx *= rm[4 * g4 + 1];
;                 a[4 * g4 + 0] = bt[4 * g4 + 0] * sfx;
;                 run *= Gs[g4] * Gp[g4];
;             }
;             C = run;
; #pragma unroll
;             for (int s2 = 0; s2 < 2; ++s2) {
;                 u32x4 pw; pw.x = cvt_pk_bf16(a[8 * s2 + 0], a[8 * s2 + 1]); pw.y = cvt_pk_bf16(a[8 * s2 + 2], a[8 * s2 + 3]); pw.z = cvt_pk_bf16(a[8 * s2 + 4], a[8 * s2 + 5]); pw.w = cvt_pk_bf16(a[8 * s2 + 6], a[8 * s2 + 7]);
;                 const bf16x8 pf = __builtin_bit_cast(bf16x8, pw);
; #pragma unroll
;                 for (int dt = 0; dt < 2; ++dt) {
;                     const int dcol = 32 * dt + 16 * ((lane >> 4) & 1) + 4 * (lane & 3);
;                     const int krow = 16 * s2 + 4 * hi + ((lane & 15) >> 2);
;                     const s16x4 t0v = __builtin_bit_cast(s16x4, __builtin_amdgcn_ds_read_tr16_b64_v4i16((LAS s16x4*)(Vb + krow * P64 + dcol * 2)));
	v_mfma_f32_32x32x16_bf16 v[2:17], v[28:31], v[20:23], v[2:17]
	s_nop 11
	v_cndmask_b32_e64 v3, v226, v3, s[38:39]
	v_exp_f32_e32 v3, v3
	v_cndmask_b32_e64 v20, v226, v4, s[40:41]
	v_cndmask_b32_e64 v5, v226, v5, s[42:43]
	v_cndmask_b32_e64 v21, v226, v6, s[44:45]
	v_add_f32_e32 v3, 1.0, v3
	v_rcp_f32_e32 v4, v3
	v_exp_f32_e32 v3, v20
	v_cndmask_b32_e64 v22, v226, v8, s[48:49]
	v_cndmask_b32_e64 v7, v226, v7, s[46:47]
	v_cndmask_b32_e64 v23, v226, v10, s[52:53]
	v_add_f32_e32 v3, 1.0, v3
	v_rcp_f32_e32 v6, v3
	v_exp_f32_e32 v3, v5
	v_cndmask_b32_e64 v25, v226, v12, s[56:57]
	v_cndmask_b32_e64 v9, v226, v9, s[50:51]
	v_cndmask_b32_e64 v24, v226, v11, s[54:55]
	v_add_f32_e32 v3, 1.0, v3
	v_rcp_f32_e32 v8, v3
	v_exp_f32_e32 v3, v21
	v_cndmask_b32_e64 v26, v226, v13, s[58:59]
	v_cndmask_b32_e64 v27, v226, v14, s[60:61]
	v_cndmask_b32_e64 v29, v226, v16, s[64:65]
	v_add_f32_e32 v3, 1.0, v3
	v_rcp_f32_e32 v10, v3
	v_exp_f32_e32 v3, v7
	v_cndmask_b32_e64 v28, v226, v15, s[62:63]
	v_cndmask_b32_e64 v30, v226, v17, s[66:67]
	v_cndmask_b32_e64 v2, v226, v2, s[36:37]
	v_add_f32_e32 v3, 1.0, v3
	v_rcp_f32_e32 v12, v3
	v_exp_f32_e32 v3, v22
	v_exp_f32_e32 v2, v2
	v_add_f32_e32 v3, 1.0, v3
	v_rcp_f32_e32 v11, v3
	v_exp_f32_e32 v3, v9
	v_add_f32_e32 v2, 1.0, v2
	v_rcp_f32_e32 v2, v2
	v_add_f32_e32 v3, 1.0, v3
	v_rcp_f32_e32 v13, v3
	v_exp_f32_e32 v3, v23
	s_nop 0
	v_add_f32_e32 v3, 1.0, v3
	v_rcp_f32_e32 v14, v3
	v_exp_f32_e32 v3, v24
	s_nop 0
	v_add_f32_e32 v3, 1.0, v3
	v_rcp_f32_e32 v16, v3
	v_exp_f32_e32 v3, v25
	v_pk_mul_f32 v[24:25], v[10:11], v[12:13]
	v_add_f32_e32 v3, 1.0, v3
	v_rcp_f32_e32 v15, v3
	v_exp_f32_e32 v3, v26
	v_pk_mul_f32 v[24:25], v[24:25], v[24:25] op_sel:[0,1] op_sel_hi:[1,0]
	v_add_f32_e32 v3, 1.0, v3
	v_rcp_f32_e32 v17, v3
	v_exp_f32_e32 v3, v27
	v_mov_b32_e32 v5, v24
	v_pk_mul_f32 v[26:27], v[14:15], v[16:17]
	v_add_f32_e32 v3, 1.0, v3
	v_rcp_f32_e32 v20, v3
	v_exp_f32_e32 v3, v28
	v_mov_b32_e32 v31, v26
	v_add_f32_e32 v3, 1.0, v3
	v_rcp_f32_e32 v22, v3
	v_exp_f32_e32 v3, v29
	s_nop 0
	v_add_f32_e32 v3, 1.0, v3
	v_rcp_f32_e32 v21, v3
	v_exp_f32_e32 v3, v30
	s_nop 0
	v_add_f32_e32 v3, 1.0, v3
	v_rcp_f32_e32 v23, v3
	v_mov_b32_e32 v3, v24
	s_nop 1
	v_permlane32_swap_b32_e32 v3, v5
	v_pk_mul_f32 v[28:29], v[20:21], v[22:23]
	v_mov_b32_e32 v30, v28
	v_mov_b32_e32 v26, v29
	v_pk_mul_f32 v[26:27], v[30:31], v[26:27]
	v_cndmask_b32_e64 v5, v3, v5, s[68:69]
	v_mov_b32_e32 v3, v27
	v_mov_b32_e32 v7, v27
	v_mov_b32_e32 v9, v26
	v_mov_b32_e32 v25, v26
	v_permlane32_swap_b32_e32 v3, v7
	s_nop 0
	v_permlane32_swap_b32_e32 v9, v25
	v_cmp_eq_u32_e64 s[72:73], v3, v27
	v_cndmask_b32_e64 v30, 1.0, v5, s[68:69]
	v_mov_b32_e32 v31, v12
	v_cndmask_b32_e64 v3, v3, v7, s[72:73]
	v_cndmask_b32_e64 v7, v9, v25, s[68:69]
	v_cndmask_b32_e64 v25, 1.0, v7, s[68:69]
	v_cndmask_b32_e64 v34, 1.0, v3, s[68:69]
	v_mul_f32_e32 v9, v26, v7
	v_mul_f32_e32 v7, v27, v3
	v_mov_b32_e32 v3, v24
	v_pk_mul_f32 v[26:27], v[6:7], v[8:9]
	v_pk_mul_f32 v[28:29], v[2:3], v[4:5]
	v_mul_f32_e32 v24, v23, v25
	v_pk_mul_f32 v[28:29], v[28:29], v[26:27]
	v_mul_f32_e32 v27, v30, v27
	v_mul_f32_e32 v26, v13, v27
	v_mul_f32_e32 v33, v11, v26
	v_mul_f32_e32 v32, v12, v33
	v_mov_b32_e32 v12, v11
	v_mov_b32_e32 v3, v28
	v_mov_b32_e32 v5, v28
	v_mov_b32_e32 v30, v10
	v_pk_add_f32 v[10:11], v[12:13], 1.0 op_sel_hi:[1,0] neg_lo:[1,0] neg_hi:[1,0]
	v_mul_f32_e32 v13, v34, v9
	v_permlane32_swap_b32_e32 v3, v5
	v_pk_add_f32 v[30:31], v[30:31], 1.0 op_sel_hi:[1,0] neg_lo:[1,0] neg_hi:[1,0]
	v_mul_f32_e32 v12, v17, v13
	v_pk_mul_f32 v[30:31], v[30:31], v[32:33]
	v_mul_f32_e32 v33, v15, v12
	v_cndmask_b32_e64 v35, v3, v5, s[68:69]
	v_pk_mul_f32 v[10:11], v[10:11], v[26:27]
	v_mov_b32_e32 v27, v16
	v_mul_f32_e32 v32, v16, v33
	v_mov_b32_e32 v16, v15
	v_cndmask_b32_e64 v3, 1.0, v35, s[68:69]
	v_mov_b32_e32 v26, v14
	v_pk_add_f32 v[14:15], v[16:17], 1.0 op_sel_hi:[1,0] neg_lo:[1,0] neg_hi:[1,0]
	v_mov_b32_e32 v7, v8
	v_pk_mul_f32 v[12:13], v[14:15], v[12:13]
	v_mul_f32_e32 v15, v21, v24
	v_mul_f32_e32 v9, v3, v29
	v_mul_f32_e32 v14, v22, v15
	v_mov_b32_e32 v16, v20
	v_mov_b32_e32 v17, v22
	v_mov_b32_e32 v22, v21
	v_pk_add_f32 v[20:21], v[6:7], 1.0 op_sel_hi:[1,0] neg_lo:[1,0] neg_hi:[1,0]
	v_mul_f32_e32 v8, v8, v9
	v_pk_mul_f32 v[20:21], v[20:21], v[8:9]
	v_mul_f32_e32 v5, v6, v8
	ds_read_b64_tr_b16 v[6:7], v209 offset:40960
	ds_read_b64_tr_b16 v[8:9], v209 offset:42112
	v_mov_b32_e32 v3, v4
	v_pk_add_f32 v[2:3], v[2:3], 1.0 op_sel_hi:[1,0] neg_lo:[1,0] neg_hi:[1,0]
	v_mul_f32_e32 v4, v4, v5
	v_pk_mul_f32 v[2:3], v[2:3], v[4:5]
	v_mul_f32_e32 v4, v28, v35
	v_mul_f32_e32 v217, v4, v29
	v_cvt_pk_bf16_f32 v2, v2, v3
	v_cvt_pk_bf16_f32 v3, v20, v21
	v_cvt_pk_bf16_f32 v4, v30, v31
	v_cvt_pk_bf16_f32 v5, v10, v11
	v_pk_add_f32 v[16:17], v[16:17], 1.0 op_sel_hi:[1,0] neg_lo:[1,0] neg_hi:[1,0]
	v_pk_add_f32 v[26:27], v[26:27], 1.0 op_sel_hi:[1,0] neg_lo:[1,0] neg_hi:[1,0]
	s_waitcnt lgkmcnt(0)
	v_mfma_f32_32x32x16_bf16 v[68:83], v[6:9], v[2:5], 0
	ds_read_b64_tr_b16 v[6:7], v209 offset:41024
	ds_read_b64_tr_b16 v[8:9], v209 offset:42176
	v_mul_f32_e64 v14, v16, v14
	v_mul_f32_e64 v15, v17, v15
	v_add_f32_e64 v16, -v22, 1.0
	v_add_f32_e64 v17, -v23, 1.0
	v_pk_mul_f32 v[26:27], v[26:27], v[32:33]
	v_pk_mul_f32 v[16:17], v[16:17], v[24:25]
	v_cmp_gt_f32_e32 vcc, s25, v217
	s_cmp_eq_u64 vcc, exec
	s_waitcnt lgkmcnt(0)
	v_mfma_f32_32x32x16_bf16 v[84:99], v[6:9], v[2:5], 0
	ds_read_b64_tr_b16 v[6:7], v209 offset:43264
	ds_read_b64_tr_b16 v[8:9], v209 offset:44416
	v_cvt_pk_bf16_f32 v2, v26, v27
	v_cvt_pk_bf16_f32 v3, v12, v13
	v_cvt_pk_bf16_f32 v4, v14, v15
	v_cvt_pk_bf16_f32 v5, v16, v17
	s_waitcnt lgkmcnt(0)
; #define LAS __attribute__((address_space(3)))
; __device__ __forceinline__ void sb_attn(Frame& F) {
;     ...
;                 for (int dt = 0; dt < 2; ++dt) {
;                     const int dcol = 32 * dt + 16 * ((lane >> 4) & 1) + 4 * (lane & 3);
;                     const int krow = 16 * s2 + 4 * hi + ((lane & 15) >> 2);
;                     const s16x4 t0v = __builtin_bit_cast(s16x4, __builtin_amdgcn_ds_read_tr16_b64_v4i16((LAS s16x4*)(Vb + krow * P64 + dcol * 2)));
;                     const s16x4 t1v = __builtin_bit_cast(s16x4, __builtin_amdgcn_ds_read_tr16_b64_v4i16((LAS s16x4*)(Vb + (krow + 8) * P64 + dcol * 2)));
;                     const bf16x8 vf = (bf16x8){t0v[0], t0v[1], t0v[2], t0v[3], t1v[0], t1v[1], t1v[2], t1v[3]};
;                     o[dt] = __builtin_amdgcn_mfma_f32_32x32x16_bf16(vf, pf, o[dt], 0, 0, 0);
;                 }
;             }
;         };
;     ...
;             const bool actU = !doneU, actL = (kb <= qL) && !doneL;
; #pragma unroll
;             for (int n = 0; n < 4; ++n) { const int idx = lane + 64 * n; *(LAS u32x4*)(Vb + (idx >> 3) * P64 + (idx & 7) * 16) = vreg[n]; }
;             if (actU) { const f32x16 sU = scores(1); weigh(sU, oU, CU, kb == qU); doneU = __all(CU < 0x1p-120f); }
;             f32x16 sL;
;             if (actL) sL = scores(0);
;             if (kb > 0) {
;                 const bf16* Kp = PROJ + (tok0 + 32 * (kb - 1) + r32) * NPROJ + C_SK + 64 * h + 8 * hi;
; #pragma unroll
;                 for (int ds = 0; ds < 4; ++ds) kf[ds] = *(const bf16x8*)(Kp + 16 * ds);
; #pragma unroll
;                 for (int n = 0; n < 4; ++n) { const int idx = lane + 64 * n; vreg[n] = *(const u32x4*)(PROJ + (tok0 + 32 * (kb - 1) + (idx >> 3)) * NPROJ + C_SV + 64 * h + 8 * (idx & 7)); }
	s_nop 0
	v_mfma_f32_32x32x16_bf16 v[68:83], v[6:9], v[2:5], v[68:83]
	ds_read_b64_tr_b16 v[6:7], v209 offset:43328
	ds_read_b64_tr_b16 v[8:9], v209 offset:44480
	s_waitcnt lgkmcnt(0)
	v_mfma_f32_32x32x16_bf16 v[84:99], v[6:9], v[2:5], v[84:99]
	v_or_b32_e32 v2, s12, v204
	v_mad_u64_u32 v[2:3], s[28:29], v2, s81, v[18:19]
	v_mad_i32_i24 v3, s11, v225, v3
	v_lshl_add_u64 v[2:3], v[2:3], 0, s[16:17]
	v_lshl_add_u64 v[2:3], v[2:3], 0, v[66:67]
	v_lshl_add_u64 v[4:5], v[2:3], 0, s[30:31]
	v_add_co_u32_e32 v2, vcc, s35, v2
	s_nop 1
	v_addc_co_u32_e32 v3, vcc, 0, v3, vcc
	global_load_dwordx4 v[164:167], v[2:3], off offset:1024
	global_load_dwordx4 v[168:171], v[4:5], off offset:32
	global_load_dwordx4 v[172:175], v[4:5], off offset:64
	global_load_dwordx4 v[176:179], v[4:5], off offset:96
	v_or_b32_e32 v2, s12, v206
	v_mad_u64_u32 v[2:3], s[28:29], v2, s81, v[18:19]
	v_mad_i32_i24 v3, s11, v225, v3
	v_lshl_add_u64 v[2:3], v[2:3], 0, s[16:17]
	v_lshl_add_u64 v[2:3], v[2:3], 0, v[214:215]
	v_add_co_u32_e32 v2, vcc, s35, v2
	s_nop 1
	v_addc_co_u32_e32 v3, vcc, 0, v3, vcc
	global_load_dwordx4 v[180:183], v[2:3], off offset:2048
	v_or_b32_e32 v2, s12, v208
	v_mad_u64_u32 v[2:3], s[28:29], v2, s81, v[18:19]
	v_mad_i32_i24 v3, s11, v225, v3
	v_lshl_add_u64 v[2:3], v[2:3], 0, s[16:17]
	v_lshl_add_u64 v[2:3], v[2:3], 0, v[214:215]
	v_add_co_u32_e32 v2, vcc, s35, v2
	s_nop 1
	v_addc_co_u32_e32 v3, vcc, 0, v3, vcc
	global_load_dwordx4 v[184:187], v[2:3], off offset:2048
	v_or_b32_e32 v2, s12, v210
	v_mad_u64_u32 v[2:3], s[28:29], v2, s81, v[18:19]
	v_mad_i32_i24 v3, s11, v225, v3
	v_lshl_add_u64 v[2:3], v[2:3], 0, s[16:17]
	v_lshl_add_u64 v[2:3], v[2:3], 0, v[214:215]
	v_add_co_u32_e32 v2, vcc, s35, v2
	s_nop 1
	v_addc_co_u32_e32 v3, vcc, 0, v3, vcc
	global_load_dwordx4 v[188:191], v[2:3], off offset:2048
	v_or_b32_e32 v2, s12, v212
	v_mad_u64_u32 v[2:3], s[12:13], v2, s81, v[18:19]
	v_mad_i32_i24 v3, s11, v225, v3
	v_lshl_add_u64 v[2:3], v[2:3], 0, s[16:17]
	v_lshl_add_u64 v[2:3], v[2:3], 0, v[214:215]
	v_add_co_u32_e32 v2, vcc, 0x1000, v2
	s_mov_b64 s[12:13], -1
	s_nop 0
	v_addc_co_u32_e32 v3, vcc, 0, v3, vcc
	global_load_dwordx4 v[192:195], v[2:3], off offset:2048
	s_waitcnt vmcnt(3)
	ds_write_b128 v207, v[180:183] offset:40960
	s_waitcnt vmcnt(2)
	ds_write_b128 v207, v[184:187] offset:42112
	s_waitcnt vmcnt(1)
	ds_write_b128 v207, v[188:191] offset:43264
	s_waitcnt vmcnt(0)
	ds_write_b128 v207, v[192:195] offset:44416
	s_cbranch_scc1 .LBB0_307
; __device__ __forceinline__ void sb_attn(Frame& F) {
;     ...
;         auto scores = [&](int up) __attribute__((always_inline)) -> f32x16 {
;             f32x16 s;
; #pragma unroll
;             for (int r = 0; r < 16; ++r) s[r] = 0.f;
; #pragma unroll
;             for (int ds = 0; ds < 4; ++ds) { const bf16x8 qf = *(const LAS bf16x8*)(Qs + ((4 * up + ds) * 64 + lane) * 16); s = __builtin_amdgcn_mfma_f32_32x32x16_bf16(kf[ds], qf, s, 0, 0, 0); }
;             return s;
;         };
;         auto weigh = [&](f32x16 s, f32x16 (&o)[2], float& C, bool diag) __attribute__((always_inline)) {
;             if (diag) {
; #pragma unroll
;                 for (int r = 0; r < 16; ++r) { const int key = (r & 3) + 8 * (r >> 2) + 4 * hi; s[r] = (key < r32) ? s[r] : -1e30f; }
;             }
;             float rm[16], bt[16];
; #pragma unroll
;             for (int r = 0; r < 16; ++r) {
;                 const float q1 = fast_rcp(1.0f + __builtin_amdgcn_exp2f(s[r]));
;                 rm[r] = q1;
;                 bt[r] = 1.0f - q1;
;             }
;             float Gs[4], Gp[4];
; #pragma unroll
;             for (int g4 = 0; g4 < 4; ++g4) { Gs[g4] = (rm[4 * g4] * rm[4 * g4 + 1]) * (rm[4 * g4 + 2] * rm[4 * g4 + 3]);
;                 const unsigned own = __builtin_bit_cast(unsigned, Gs[g4]);
;                 const u32x2 sw = __builtin_amdgcn_permlane32_swap(own, own, false, false);
;                 const unsigned r0 = sw.x, r1 = sw.y;
;                 Gp[g4] = __builtin_bit_cast(float, (r0 == own) ? r1 : r0); }
;             float run = C;
;             float a[16];
; #pragma unroll
;     ...
;                 float sfx = run * (hi == 0 ? Gp[g4] : 1.0f);
;                 a[4 * g4 + 3] = bt[4 * g4 + 3] * sfx; sfx *= rm[4 * g4 + 3];
;                 a[4 * g4 + 2] = bt[4 * g4 + 2] * sfx; sfx *= rm[4 * g4 + 2];
;                 a[4 * g4 + 1] = bt[4 * g4 + 1] * sfx; sfx *= rm[4 * g4 + 1];
;                 a[4 * g4 + 0] = bt[4 * g4 + 0] * sfx;
;                 run *= Gs[g4] * Gp[g4];
;             }
;             C = run;
; #pragma unroll
;             for (int s2 = 0; s2 < 2; ++s2) {
;                 u32x4 pw; pw.x = cvt_pk_bf16(a[8 * s2 + 0], a[8 * s2 + 1]); pw.y = cvt_pk_bf16(a[8 * s2 + 2], a[8 * s2 + 3]); pw.z = cvt_pk_bf16(a[8 * s2 + 4], a[8 * s2 + 5]); pw.w = cvt_pk_bf16(a[8 * s2 + 6], a[8 * s2 + 7]);
;                 const bf16x8 pf = __builtin_bit_cast(bf16x8, pw);
	ds_read_b128 v[2:5], v211 offset:4096
	ds_read_b128 v[18:21], v211 offset:5120
	s_waitcnt lgkmcnt(1)
	v_mfma_f32_32x32x16_bf16 v[2:17], v[164:167], v[2:5], 0
	s_waitcnt lgkmcnt(0)
	v_mfma_f32_32x32x16_bf16 v[2:17], v[168:171], v[18:21], v[2:17]
	ds_read_b128 v[18:21], v211 offset:6144
	ds_read_b128 v[22:25], v211 offset:7168
	s_waitcnt lgkmcnt(1)
	v_mfma_f32_32x32x16_bf16 v[2:17], v[172:175], v[18:21], v[2:17]
	s_waitcnt lgkmcnt(0)
	v_mfma_f32_32x32x16_bf16 v[2:17], v[176:179], v[22:25], v[2:17]
	s_nop 11
	v_exp_f32_e32 v3, v3
	v_exp_f32_e32 v5, v5
	v_exp_f32_e32 v6, v6
	v_exp_f32_e32 v21, v13
	v_exp_f32_e32 v8, v8
	v_exp_f32_e32 v14, v14
	v_exp_f32_e32 v7, v7
	v_exp_f32_e32 v12, v12
	v_add_f32_e32 v3, 1.0, v3
	v_add_f32_e32 v5, 1.0, v5
	v_add_f32_e32 v13, 1.0, v6
	v_rcp_f32_e32 v6, v3
	v_add_f32_e32 v3, 1.0, v21
	v_exp_f32_e32 v9, v9
	v_add_f32_e32 v18, 1.0, v8
	v_rcp_f32_e32 v8, v5
	v_rcp_f32_e32 v21, v3
	v_exp_f32_e32 v3, v15
	v_add_f32_e32 v5, 1.0, v14
	v_exp_f32_e32 v10, v10
	v_exp_f32_e32 v11, v11
	v_add_f32_e32 v7, 1.0, v7
	v_rcp_f32_e32 v14, v5
	v_exp_f32_e32 v5, v16
	v_add_f32_e32 v22, 1.0, v12
	v_rcp_f32_e32 v12, v7
	v_exp_f32_e32 v7, v17
	v_add_f32_e32 v9, 1.0, v9
	v_add_f32_e32 v3, 1.0, v3
	v_add_f32_e32 v19, 1.0, v10
	v_add_f32_e32 v20, 1.0, v11
	v_rcp_f32_e32 v10, v13
	v_rcp_f32_e32 v11, v18
	v_rcp_f32_e32 v13, v9
	v_rcp_f32_e32 v16, v3
	v_add_f32_e32 v3, 1.0, v5
	v_rcp_f32_e32 v15, v3
	v_add_f32_e32 v3, 1.0, v7
	v_rcp_f32_e32 v18, v19
	v_rcp_f32_e32 v20, v20
	v_rcp_f32_e32 v19, v22
	v_rcp_f32_e32 v17, v3
	v_pk_mul_f32 v[22:23], v[10:11], v[12:13]
	v_exp_f32_e32 v2, v2
	v_pk_mul_f32 v[22:23], v[22:23], v[22:23] op_sel:[0,1] op_sel_hi:[1,0]
	v_pk_mul_f32 v[24:25], v[18:19], v[20:21]
	v_mov_b32_e32 v3, v22
	v_mov_b32_e32 v5, v22
	v_pk_mul_f32 v[26:27], v[14:15], v[16:17]
	v_exp_f32_e32 v4, v4
	v_permlane32_swap_b32_e32 v3, v5
	v_mov_b32_e32 v28, v26
	v_mov_b32_e32 v29, v24
	v_mov_b32_e32 v24, v27
	v_pk_mul_f32 v[24:25], v[28:29], v[24:25]
	v_add_f32_e32 v2, 1.0, v2
	v_cndmask_b32_e64 v7, v3, v5, s[68:69]
	v_mov_b32_e32 v3, v25
	v_mov_b32_e32 v5, v25
	s_nop 1
	v_permlane32_swap_b32_e32 v3, v5
	v_mov_b32_e32 v9, v24
	v_mov_b32_e32 v23, v24
	v_add_f32_e32 v4, 1.0, v4
	s_nop 0
	v_permlane32_swap_b32_e32 v9, v23
	v_rcp_f32_e32 v2, v2
	v_rcp_f32_e32 v4, v4
	v_cndmask_b32_e64 v3, v3, v5, s[68:69]
	v_cndmask_b32_e64 v31, 1.0, v3, s[68:69]
	v_cndmask_b32_e64 v26, 1.0, v7, s[68:69]
	v_cndmask_b32_e64 v5, v9, v23, s[68:69]
	v_cndmask_b32_e64 v30, 1.0, v5, s[68:69]
	v_mul_f32_e32 v5, v24, v5
	v_mul_f32_e32 v9, v217, v5
	v_mul_f32_e32 v5, v25, v3
	v_mov_b32_e32 v3, v22
	v_pk_mul_f32 v[24:25], v[4:5], v[8:9]
	v_pk_mul_f32 v[22:23], v[2:3], v[6:7]
	v_mov_b32_e32 v27, v12
	v_pk_mul_f32 v[22:23], v[22:23], v[24:25]
	v_mul_f32_e32 v25, v26, v25
	v_mul_f32_e32 v24, v13, v25
	v_mov_b32_e32 v3, v22
	v_mov_b32_e32 v5, v22
	v_mul_f32_e32 v29, v11, v24
	s_nop 0
	v_permlane32_swap_b32_e32 v3, v5
	v_mul_f32_e32 v28, v12, v29
	v_mov_b32_e32 v12, v11
	v_mov_b32_e32 v26, v10
	v_pk_add_f32 v[10:11], v[12:13], 1.0 op_sel_hi:[1,0] neg_lo:[1,0] neg_hi:[1,0]
	v_mul_f32_e32 v13, v31, v9
	v_cndmask_b32_e64 v32, v3, v5, s[68:69]
	v_pk_add_f32 v[26:27], v[26:27], 1.0 op_sel_hi:[1,0] neg_lo:[1,0] neg_hi:[1,0]
	v_mul_f32_e32 v12, v21, v13
	v_cndmask_b32_e64 v3, 1.0, v32, s[68:69]
	v_pk_mul_f32 v[26:27], v[26:27], v[28:29]
	v_mul_f32_e32 v29, v19, v12
	v_pk_mul_f32 v[10:11], v[10:11], v[24:25]
	v_mov_b32_e32 v25, v20
	v_mul_f32_e32 v28, v20, v29
	v_mov_b32_e32 v20, v19
	v_mul_f32_e32 v9, v3, v23
	v_mov_b32_e32 v24, v18
	v_pk_add_f32 v[18:19], v[20:21], 1.0 op_sel_hi:[1,0] neg_lo:[1,0] neg_hi:[1,0]
	v_mov_b32_e32 v5, v8
	v_mul_f32_e32 v8, v8, v9
	v_pk_add_f32 v[24:25], v[24:25], 1.0 op_sel_hi:[1,0] neg_lo:[1,0] neg_hi:[1,0]
	v_pk_mul_f32 v[18:19], v[18:19], v[12:13]
	v_mov_b32_e32 v12, v14
	v_mov_b32_e32 v13, v16
	v_mov_b32_e32 v3, v6
	v_mul_f32_e32 v7, v4, v8
	v_pk_mul_f32 v[24:25], v[24:25], v[28:29]
	v_mul_f32_e32 v21, v217, v30
	v_pk_add_f32 v[28:29], v[12:13], 1.0 op_sel_hi:[1,0] neg_lo:[1,0] neg_hi:[1,0]
	v_pk_add_f32 v[12:13], v[4:5], 1.0 op_sel_hi:[1,0] neg_lo:[1,0] neg_hi:[1,0]
	v_pk_add_f32 v[30:31], v[2:3], 1.0 op_sel_hi:[1,0] neg_lo:[1,0] neg_hi:[1,0]
	v_mul_f32_e32 v6, v6, v7
	v_pk_mul_f32 v[12:13], v[12:13], v[8:9]
	ds_read_b64_tr_b16 v[2:3], v209 offset:40960
	ds_read_b64_tr_b16 v[4:5], v209 offset:42112
	v_pk_mul_f32 v[6:7], v[30:31], v[6:7]
	v_cvt_pk_bf16_f32 v9, v10, v11
	v_cvt_pk_bf16_f32 v6, v6, v7
	v_cvt_pk_bf16_f32 v7, v12, v13
	ds_read_b64_tr_b16 v[12:13], v209 offset:42176
	ds_read_b64_tr_b16 v[10:11], v209 offset:41024
	v_mul_f32_e32 v20, v17, v21
	v_cvt_pk_bf16_f32 v8, v26, v27
	s_waitcnt lgkmcnt(2)
	s_nop 0
	v_mfma_f32_32x32x16_bf16 v[68:83], v[2:5], v[6:9], v[68:83]
	v_mul_f32_e32 v3, v15, v20
	v_mul_f32_e32 v2, v16, v3
	v_mov_b32_e32 v16, v15
	v_add_f32_e64 v14, -v16, 1.0
	v_add_f32_e64 v15, -v17, 1.0
	v_pk_mul_f32 v[26:27], v[28:29], v[2:3]
	ds_read_b64_tr_b16 v[2:3], v209 offset:43264
	ds_read_b64_tr_b16 v[4:5], v209 offset:44416
	s_waitcnt lgkmcnt(2)
	v_mfma_f32_32x32x16_bf16 v[84:99], v[10:13], v[6:9], v[84:99]
	v_mul_f32_e64 v10, v14, v20
	v_mul_f32_e64 v11, v15, v21
	v_cvt_pk_bf16_f32 v6, v24, v25
	v_cvt_pk_bf16_f32 v9, v10, v11
	ds_read_b64_tr_b16 v[12:13], v209 offset:44480
	ds_read_b64_tr_b16 v[10:11], v209 offset:43328
	v_cvt_pk_bf16_f32 v7, v18, v19
	v_cvt_pk_bf16_f32 v8, v26, v27
	s_waitcnt lgkmcnt(2)
	s_nop 0
	v_mfma_f32_32x32x16_bf16 v[68:83], v[2:5], v[6:9], v[68:83]
	v_mul_f32_e32 v2, v22, v32
	v_mul_f32_e32 v217, v2, v23
	v_cmp_gt_f32_e32 vcc, s25, v217
	s_cmp_eq_u64 vcc, exec
	s_cselect_b64 s[12:13], -1, 0
	s_waitcnt lgkmcnt(0)
	v_mfma_f32_32x32x16_bf16 v[84:99], v[10:13], v[6:9], v[84:99]

; __device__ __forceinline__ void sb_attn(Frame& F) {
;     ...
;         auto weigh = [&](f32x16 s, f32x16 (&o)[2], float& C, bool diag) __attribute__((always_inline)) {
;             if (diag) {
; #pragma unroll
;                 for (int r = 0; r < 16; ++r) { const int key = (r & 3) + 8 * (r >> 2) + 4 * hi; s[r] = (key < r32) ? s[r] : -1e30f; }
;             }
;             float rm[16], bt[16];
; #pragma unroll
;             for (int r = 0; r < 16; ++r) {
;                 const float q1 = fast_rcp(1.0f + __builtin_amdgcn_exp2f(s[r]));
;                 rm[r] = q1;
;                 bt[r] = 1.0f - q1;
;             }
;             float Gs[4], Gp[4];
; #pragma unroll
;             for (int g4 = 0; g4 < 4; ++g4) { Gs[g4] = (rm[4 * g4] * rm[4 * g4 + 1]) * (rm[4 * g4 + 2] * rm[4 * g4 + 3]);
;                 const unsigned own = __builtin_bit_cast(unsigned, Gs[g4]);
;                 const u32x2 sw = __builtin_amdgcn_permlane32_swap(own, own, false, false);
;                 const unsigned r0 = sw.x, r1 = sw.y;
;                 Gp[g4] = __builtin_bit_cast(float, (r0 == own) ? r1 : r0); }
;             float run = C;
;             float a[16];
; #pragma unroll
;     ...
;                 float sfx = run * (hi == 0 ? Gp[g4] : 1.0f);
;                 a[4 * g4 + 3] = bt[4 * g4 + 3] * sfx; sfx *= rm[4 * g4 + 3];
;                 a[4 * g4 + 2] = bt[4 * g4 + 2] * sfx; sfx *= rm[4 * g4 + 2];
;                 a[4 * g4 + 1] = bt[4 * g4 + 1] * sfx; sfx *= rm[4 * g4 + 1];
;                 a[4 * g4 + 0] = bt[4 * g4 + 0] * sfx;
;                 run *= Gs[g4] * Gp[g4];
;             }
;             C = run;
; #pragma unroll
;             for (int s2 = 0; s2 < 2; ++s2) {
;                 u32x4 pw; pw.x = cvt_pk_bf16(a[8 * s2 + 0], a[8 * s2 + 1]); pw.y = cvt_pk_bf16(a[8 * s2 + 2], a[8 * s2 + 3]); pw.z = cvt_pk_bf16(a[8 * s2 + 4], a[8 * s2 + 5]); pw.w = cvt_pk_bf16(a[8 * s2 + 6], a[8 * s2 + 7]);
;                 const bf16x8 pf = __builtin_bit_cast(bf16x8, pw);
; #pragma unroll
;                 for (int dt = 0; dt < 2; ++dt) {
;                     const int dcol = 32 * dt + 16 * ((lane >> 4) & 1) + 4 * (lane & 3);
;                     const int krow = 16 * s2 + 4 * hi + ((lane & 15) >> 2);
;                     const s16x4 t0v = __builtin_bit_cast(s16x4, __builtin_amdgcn_ds_read_tr16_b64_v4i16((LAS s16x4*)(Vb + krow * P64 + dcol * 2)));
.LBB0_309:
	s_nop 10
	v_cndmask_b32_e64 v3, v226, v101, s[38:39]
	v_exp_f32_e32 v3, v3
	v_cndmask_b32_e64 v5, v226, v103, s[42:43]
	v_cndmask_b32_e64 v7, v226, v104, s[44:45]
	v_cndmask_b32_e64 v9, v226, v105, s[46:47]
	v_add_f32_e32 v3, 1.0, v3
	v_rcp_f32_e32 v6, v3
	v_exp_f32_e32 v3, v5
	v_exp_f32_e32 v5, v7
	v_cndmask_b32_e64 v11, v226, v106, s[48:49]
	v_cndmask_b32_e64 v13, v226, v107, s[50:51]
	v_add_f32_e32 v3, 1.0, v3
	v_rcp_f32_e32 v8, v3
	v_exp_f32_e32 v3, v9
	v_add_f32_e32 v5, 1.0, v5
	v_rcp_f32_e32 v10, v5
	v_exp_f32_e32 v5, v11
	v_add_f32_e32 v3, 1.0, v3
	v_cndmask_b32_e64 v14, v226, v108, s[52:53]
	v_rcp_f32_e32 v12, v3
	v_exp_f32_e32 v3, v13
	v_add_f32_e32 v5, 1.0, v5
	v_rcp_f32_e32 v11, v5
	v_exp_f32_e32 v5, v14
	v_cndmask_b32_e64 v15, v226, v109, s[54:55]
	v_add_f32_e32 v3, 1.0, v3
	v_cndmask_b32_e64 v16, v226, v110, s[56:57]
	v_rcp_f32_e32 v13, v3
	v_exp_f32_e32 v3, v15
	v_add_f32_e32 v5, 1.0, v5
	v_rcp_f32_e32 v14, v5
	v_exp_f32_e32 v5, v16
	v_cndmask_b32_e64 v17, v226, v111, s[58:59]
	v_add_f32_e32 v3, 1.0, v3
	v_cndmask_b32_e64 v18, v226, v112, s[60:61]
	v_rcp_f32_e32 v16, v3
	v_exp_f32_e32 v3, v17
	v_add_f32_e32 v5, 1.0, v5
	v_rcp_f32_e32 v15, v5
	v_exp_f32_e32 v5, v18
	v_cndmask_b32_e64 v19, v226, v113, s[62:63]
	v_add_f32_e32 v3, 1.0, v3
	v_cndmask_b32_e64 v20, v226, v114, s[64:65]
	v_rcp_f32_e32 v17, v3
	v_exp_f32_e32 v3, v19
	v_add_f32_e32 v5, 1.0, v5
	v_cndmask_b32_e64 v21, v226, v115, s[66:67]
	v_rcp_f32_e32 v26, v5
	v_exp_f32_e32 v5, v20
	v_exp_f32_e32 v7, v21
	v_add_f32_e32 v3, 1.0, v3
	v_rcp_f32_e32 v28, v3
	v_add_f32_e32 v3, 1.0, v5
	v_rcp_f32_e32 v27, v3
	v_add_f32_e32 v3, 1.0, v7
	v_rcp_f32_e32 v29, v3
	v_pk_mul_f32 v[18:19], v[10:11], v[12:13]
	v_cndmask_b32_e64 v2, v226, v100, s[36:37]
	v_cndmask_b32_e64 v4, v226, v102, s[40:41]
	v_pk_mul_f32 v[18:19], v[18:19], v[18:19] op_sel:[0,1] op_sel_hi:[1,0]
	v_exp_f32_e32 v2, v2
	v_exp_f32_e32 v4, v4
	v_mov_b32_e32 v3, v18
	v_mov_b32_e32 v5, v18
	v_pk_mul_f32 v[20:21], v[14:15], v[16:17]
	v_pk_mul_f32 v[22:23], v[26:27], v[28:29]
	v_permlane32_swap_b32_e32 v3, v5
	v_mov_b32_e32 v24, v22
	v_mov_b32_e32 v25, v20
	v_mov_b32_e32 v20, v23
	v_pk_mul_f32 v[20:21], v[24:25], v[20:21]
	v_add_f32_e32 v2, 1.0, v2
	v_cndmask_b32_e64 v7, v3, v5, s[68:69]
	v_mov_b32_e32 v3, v21
	v_mov_b32_e32 v5, v21
	v_add_f32_e32 v4, 1.0, v4
	s_nop 0
	v_permlane32_swap_b32_e32 v3, v5
	v_mov_b32_e32 v9, v20
	v_mov_b32_e32 v19, v20
	v_rcp_f32_e32 v2, v2
	v_rcp_f32_e32 v4, v4
	v_permlane32_swap_b32_e32 v9, v19
	v_cndmask_b32_e64 v22, 1.0, v7, s[68:69]
	v_mov_b32_e32 v32, v26
	v_cndmask_b32_e64 v3, v3, v5, s[68:69]
	v_cndmask_b32_e64 v24, 1.0, v3, s[68:69]
	v_mov_b32_e32 v33, v28
	v_cndmask_b32_e64 v5, v9, v19, s[68:69]
	v_cndmask_b32_e64 v39, 1.0, v5, s[68:69]
	v_mul_f32_e32 v9, v20, v5
	v_mul_f32_e32 v5, v21, v3
	v_mov_b32_e32 v3, v18
	v_pk_mul_f32 v[20:21], v[4:5], v[8:9]
	v_pk_mul_f32 v[18:19], v[2:3], v[6:7]
	v_mul_f32_e32 v38, v29, v39
	v_pk_mul_f32 v[46:47], v[18:19], v[20:21]
	v_mul_f32_e32 v19, v22, v21
	v_mul_f32_e32 v18, v13, v19
	v_mov_b32_e32 v3, v46
	v_mov_b32_e32 v5, v46
	v_mul_f32_e32 v23, v11, v18
	s_nop 0
	v_permlane32_swap_b32_e32 v3, v5
	v_mov_b32_e32 v21, v12
	v_mul_f32_e32 v22, v12, v23
	v_mov_b32_e32 v12, v11
	v_mov_b32_e32 v20, v10
	v_pk_add_f32 v[10:11], v[12:13], 1.0 op_sel_hi:[1,0] neg_lo:[1,0] neg_hi:[1,0]
	v_mul_f32_e32 v13, v24, v9
	v_cndmask_b32_e64 v50, v3, v5, s[68:69]
	v_pk_add_f32 v[20:21], v[20:21], 1.0 op_sel_hi:[1,0] neg_lo:[1,0] neg_hi:[1,0]
	v_mul_f32_e32 v12, v17, v13
	v_cndmask_b32_e64 v3, 1.0, v50, s[68:69]
	v_pk_mul_f32 v[20:21], v[20:21], v[22:23]
	v_mul_f32_e32 v23, v15, v12
	v_pk_mul_f32 v[10:11], v[10:11], v[18:19]
	v_mov_b32_e32 v18, v14
	v_mov_b32_e32 v19, v16
	v_mul_f32_e32 v22, v16, v23
	v_mov_b32_e32 v16, v15
	v_mul_f32_e32 v9, v3, v47
	v_pk_add_f32 v[18:19], v[18:19], 1.0 op_sel_hi:[1,0] neg_lo:[1,0] neg_hi:[1,0]
	v_pk_add_f32 v[14:15], v[16:17], 1.0 op_sel_hi:[1,0] neg_lo:[1,0] neg_hi:[1,0]
	v_mov_b32_e32 v5, v8
	v_mul_f32_e32 v8, v8, v9
	v_mov_b32_e32 v3, v6
	v_pk_mul_f32 v[40:41], v[18:19], v[22:23]
	v_pk_mul_f32 v[42:43], v[14:15], v[12:13]
	v_pk_add_f32 v[12:13], v[4:5], 1.0 op_sel_hi:[1,0] neg_lo:[1,0] neg_hi:[1,0]
	v_pk_add_f32 v[14:15], v[2:3], 1.0 op_sel_hi:[1,0] neg_lo:[1,0] neg_hi:[1,0]
	v_mul_f32_e32 v7, v4, v8
	ds_read_b64_tr_b16 v[2:3], v209 offset:40960
	ds_read_b64_tr_b16 v[4:5], v209 offset:42112
	ds_read_b64_tr_b16 v[24:25], v209 offset:42176
	ds_read_b64_tr_b16 v[22:23], v209 offset:41024
	v_mul_f32_e32 v6, v6, v7
	v_mul_f32_e32 v31, v27, v38
	v_pk_mul_f32 v[12:13], v[12:13], v[8:9]
	v_pk_mul_f32 v[6:7], v[14:15], v[6:7]
	v_mul_f32_e32 v30, v28, v31
	v_cvt_pk_bf16_f32 v18, v6, v7
	v_cvt_pk_bf16_f32 v19, v12, v13
	v_cvt_pk_bf16_f32 v20, v20, v21
	v_cvt_pk_bf16_f32 v21, v10, v11
	v_pk_add_f32 v[32:33], v[32:33], 1.0 op_sel_hi:[1,0] neg_lo:[1,0] neg_hi:[1,0]
	v_mov_b32_e32 v28, v27
	s_waitcnt lgkmcnt(2)
	v_mfma_f32_32x32x16_bf16 v[2:17], v[2:5], v[18:21], 0
	v_mul_f32_e64 v44, v32, v30
	v_mul_f32_e64 v45, v33, v31
	v_add_f32_e64 v48, -v28, 1.0
	v_add_f32_e64 v49, -v29, 1.0
	ds_read_b64_tr_b16 v[34:35], v209 offset:43264
	ds_read_b64_tr_b16 v[36:37], v209 offset:44416
	v_pk_mul_f32 v[48:49], v[48:49], v[38:39]
	v_cvt_pk_bf16_f32 v38, v40, v41
	v_cvt_pk_bf16_f32 v39, v42, v43
	v_cvt_pk_bf16_f32 v40, v44, v45
	s_waitcnt lgkmcnt(2)
	v_mfma_f32_32x32x16_bf16 v[18:33], v[22:25], v[18:21], 0
	ds_read_b64_tr_b16 v[44:45], v209 offset:44480
	ds_read_b64_tr_b16 v[42:43], v209 offset:43328
	v_cvt_pk_bf16_f32 v41, v48, v49
	s_waitcnt lgkmcnt(2)
	s_nop 0
	v_mfma_f32_32x32x16_bf16 v[2:17], v[34:37], v[38:41], v[2:17]
	v_mul_f32_e32 v34, v46, v50
	v_mul_f32_e32 v231, v34, v47
	v_cmp_gt_f32_e32 vcc, s25, v231
	s_cmp_eq_u64 vcc, exec
	s_cselect_b64 s[72:73], -1, 0
	s_and_b64 s[24:25], s[12:13], s[72:73]
	s_or_b64 s[24:25], s[90:91], s[24:25]
	s_waitcnt lgkmcnt(0)
	v_mfma_f32_32x32x16_bf16 v[18:33], v[42:45], v[38:41], v[18:33]
	s_andn2_b64 vcc, exec, s[24:25]
	s_mov_b64 s[24:25], -1
	s_cbranch_vccz .LBB0_321
; #define LAS __attribute__((address_space(3)))
; __device__ __forceinline__ void sb_attn(Frame& F) {
;     ...
;             const bool actU = !doneU, actL = (kb <= qL) && !doneL;
; #pragma unroll
;             for (int n = 0; n < 4; ++n) { const int idx = lane + 64 * n; *(LAS u32x4*)(Vb + (idx >> 3) * P64 + (idx & 7) * 16) = vreg[n]; }
;             if (actU) { const f32x16 sU = scores(1); weigh(sU, oU, CU, kb == qU); doneU = __all(CU < 0x1p-120f); }
;             f32x16 sL;
;             if (actL) sL = scores(0);
;             if (kb > 0) {
;                 const bf16* Kp = PROJ + (tok0 + 32 * (kb - 1) + r32) * NPROJ + C_SK + 64 * h + 8 * hi;
; #pragma unroll
;                 for (int ds = 0; ds < 4; ++ds) kf[ds] = *(const bf16x8*)(Kp + 16 * ds);
; #pragma unroll
;                 for (int n = 0; n < 4; ++n) { const int idx = lane + 64 * n; vreg[n] = *(const u32x4*)(PROJ + (tok0 + 32 * (kb - 1) + (idx >> 3)) * NPROJ + C_SV + 64 * h + 8 * (idx & 7)); }
;             }
;             if (actL) { weigh(sL, oL, CL, kb == qL); doneL = __all(CL < 0x1p-120f); }
;             if (doneU && doneL) break;
	s_bfe_u32 s25, s7, 0x60001
	s_lshl_b32 s24, s25, 1
	s_lshl_b32 s25, s25, 6
	v_mov_b64_e32 v[130:131], v[98:99]
	v_mov_b64_e32 v[146:147], v[82:83]
	s_mov_b32 s30, 0x3800000
	s_add_i32 s24, s24, -1
	s_sub_i32 s25, s25, 64
	v_mov_b64_e32 v[128:129], v[96:97]
	v_mov_b64_e32 v[126:127], v[94:95]
	v_mov_b64_e32 v[124:125], v[92:93]
	v_mov_b64_e32 v[122:123], v[90:91]
	v_mov_b64_e32 v[120:121], v[88:89]
	v_mov_b64_e32 v[118:119], v[86:87]
	v_mov_b64_e32 v[116:117], v[84:85]
	v_mov_b64_e32 v[144:145], v[80:81]
	v_mov_b64_e32 v[142:143], v[78:79]
	v_mov_b64_e32 v[140:141], v[76:77]
	v_mov_b64_e32 v[138:139], v[74:75]
	v_mov_b64_e32 v[136:137], v[72:73]
	v_mov_b64_e32 v[134:135], v[70:71]
	v_mov_b64_e32 v[132:133], v[68:69]
	v_mov_b32_e32 v34, v2
	v_mov_b32_e32 v35, v3
	v_mov_b32_e32 v36, v4
	v_mov_b32_e32 v37, v5
	v_mov_b32_e32 v38, v6
	v_mov_b32_e32 v39, v7
	v_mov_b32_e32 v40, v8
	v_mov_b32_e32 v41, v9
	v_mov_b32_e32 v42, v10
	v_mov_b32_e32 v43, v11
	v_mov_b32_e32 v44, v12
	v_mov_b32_e32 v45, v13
	v_mov_b32_e32 v46, v14
	v_mov_b32_e32 v47, v15
	v_mov_b32_e32 v48, v16
	v_mov_b32_e32 v49, v17
	v_mov_b32_e32 v50, v18
	v_mov_b32_e32 v51, v19
	v_mov_b32_e32 v52, v20
	v_mov_b32_e32 v53, v21
	v_mov_b32_e32 v54, v22
	v_mov_b32_e32 v55, v23
	v_mov_b32_e32 v56, v24
	v_mov_b32_e32 v57, v25
	v_mov_b32_e32 v58, v26
	v_mov_b32_e32 v59, v27
	v_mov_b32_e32 v60, v28
	v_mov_b32_e32 v61, v29
	v_mov_b32_e32 v62, v30
	v_mov_b32_e32 v63, v31
	v_mov_b32_e32 v64, v32
	v_mov_b32_e32 v65, v33
	s_add_i32 s100, s10, s25
	s_mul_i32 s100, s100, s81
	s_add_u32 s100, s8, s100
	s_addc_u32 s101, s9, 0
	s_add_u32 s100, s100, s16
	s_addc_u32 s101, s101, s17
	s_add_u32 s100, s100, 0x39000
	s_addc_u32 s101, s101, 0
	v_mad_u32_u24 v239, v204, s81, v66
	v_mad_u32_u24 v240, v206, s81, v214
	v_mad_u32_u24 v241, v208, s81, v214
	v_mad_u32_u24 v242, v210, s81, v214
	v_mad_u32_u24 v243, v212, s81, v214
	s_branch .LBB0_312

; __device__ __forceinline__ void sb_attn(Frame& F) {
;     ...
;             for (int ds = 0; ds < 4; ++ds) { const bf16x8 qf = *(const LAS bf16x8*)(Qs + ((4 * up + ds) * 64 + lane) * 16); s = __builtin_amdgcn_mfma_f32_32x32x16_bf16(kf[ds], qf, s, 0, 0, 0); }
;             return s;
;         };
;         auto weigh = [&](f32x16 s, f32x16 (&o)[2], float& C, bool diag) __attribute__((always_inline)) {
;             if (diag) {
; #pragma unroll
;                 for (int r = 0; r < 16; ++r) { const int key = (r & 3) + 8 * (r >> 2) + 4 * hi; s[r] = (key < r32) ? s[r] : -1e30f; }
;             }
;             float rm[16], bt[16];
; #pragma unroll
;             for (int r = 0; r < 16; ++r) {
;                 const float q1 = fast_rcp(1.0f + __builtin_amdgcn_exp2f(s[r]));
;                 rm[r] = q1;
;                 bt[r] = 1.0f - q1;
;             }
;             float Gs[4], Gp[4];
; #pragma unroll
;             for (int g4 = 0; g4 < 4; ++g4) { Gs[g4] = (rm[4 * g4] * rm[4 * g4 + 1]) * (rm[4 * g4 + 2] * rm[4 * g4 + 3]);
;                 const unsigned own = __builtin_bit_cast(unsigned, Gs[g4]);
;                 const u32x2 sw = __builtin_amdgcn_permlane32_swap(own, own, false, false);
;                 const unsigned r0 = sw.x, r1 = sw.y;
;                 Gp[g4] = __builtin_bit_cast(float, (r0 == own) ? r1 : r0); }
;             float run = C;
;             float a[16];
; #pragma unroll
;     ...
;                 float sfx = run * (hi == 0 ? Gp[g4] : 1.0f);
;                 a[4 * g4 + 3] = bt[4 * g4 + 3] * sfx; sfx *= rm[4 * g4 + 3];
;                 a[4 * g4 + 2] = bt[4 * g4 + 2] * sfx; sfx *= rm[4 * g4 + 2];
;                 a[4 * g4 + 1] = bt[4 * g4 + 1] * sfx; sfx *= rm[4 * g4 + 1];
;                 a[4 * g4 + 0] = bt[4 * g4 + 0] * sfx;
;                 run *= Gs[g4] * Gp[g4];
;             }
;             C = run;
; #pragma unroll
;             for (int s2 = 0; s2 < 2; ++s2) {
;                 u32x4 pw; pw.x = cvt_pk_bf16(a[8 * s2 + 0], a[8 * s2 + 1]); pw.y = cvt_pk_bf16(a[8 * s2 + 2], a[8 * s2 + 3]); pw.z = cvt_pk_bf16(a[8 * s2 + 4], a[8 * s2 + 5]); pw.w = cvt_pk_bf16(a[8 * s2 + 6], a[8 * s2 + 7]);
;                 const bf16x8 pf = __builtin_bit_cast(bf16x8, pw);
; #pragma unroll
;                 for (int dt = 0; dt < 2; ++dt) {
;                     const int dcol = 32 * dt + 16 * ((lane >> 4) & 1) + 4 * (lane & 3);
.LBB0_312:
	s_mov_b64 s[28:29], s[12:13]
	s_mov_b64 s[12:13], -1
	s_and_b64 vcc, exec, s[28:29]
	s_waitcnt vmcnt(3)
	ds_write_b128 v207, v[180:183] offset:40960
	s_waitcnt vmcnt(2)
	ds_write_b128 v207, v[184:187] offset:42112
	s_waitcnt vmcnt(1)
	ds_write_b128 v207, v[188:191] offset:43264
	s_waitcnt vmcnt(0)
	ds_write_b128 v207, v[192:195] offset:44416
	s_cbranch_vccnz .LBB0_314
	ds_read_b128 v[148:151], v211 offset:4096
	ds_read_b128 v[196:199], v211 offset:5120
	s_waitcnt lgkmcnt(1)
	v_mfma_f32_32x32x16_bf16 v[148:163], v[164:167], v[148:151], 0
	s_waitcnt lgkmcnt(0)
	v_mfma_f32_32x32x16_bf16 v[148:163], v[168:171], v[196:199], v[148:163]
	ds_read_b128 v[196:199], v211 offset:6144
	ds_read_b128 v[200:203], v211 offset:7168
	s_waitcnt lgkmcnt(1)
	v_mfma_f32_32x32x16_bf16 v[148:163], v[172:175], v[196:199], v[148:163]
	s_waitcnt lgkmcnt(0)
	v_mfma_f32_32x32x16_bf16 v[148:163], v[176:179], v[200:203], v[148:163]
	s_nop 11
	v_exp_f32_e32 v149, v149
	v_exp_f32_e32 v151, v151
	v_exp_f32_e32 v152, v152
	v_exp_f32_e32 v199, v159
	v_exp_f32_e32 v154, v154
	v_exp_f32_e32 v160, v160
	v_exp_f32_e32 v153, v153
	v_exp_f32_e32 v158, v158
	v_add_f32_e32 v149, 1.0, v149
	v_add_f32_e32 v151, 1.0, v151
	v_add_f32_e32 v159, 1.0, v152
	v_rcp_f32_e32 v152, v149
	v_add_f32_e32 v149, 1.0, v199
	v_exp_f32_e32 v155, v155
	v_add_f32_e32 v196, 1.0, v154
	v_rcp_f32_e32 v154, v151
	v_rcp_f32_e32 v199, v149
	v_exp_f32_e32 v149, v161
	v_add_f32_e32 v151, 1.0, v160
	v_exp_f32_e32 v156, v156
	v_exp_f32_e32 v157, v157
	v_add_f32_e32 v153, 1.0, v153
	v_rcp_f32_e32 v160, v151
	v_exp_f32_e32 v151, v162
	v_add_f32_e32 v200, 1.0, v158
	v_rcp_f32_e32 v158, v153
	v_exp_f32_e32 v153, v163
	v_add_f32_e32 v155, 1.0, v155
	v_add_f32_e32 v149, 1.0, v149
	v_add_f32_e32 v197, 1.0, v156
	v_add_f32_e32 v198, 1.0, v157
	v_rcp_f32_e32 v156, v159
	v_rcp_f32_e32 v157, v196
	v_rcp_f32_e32 v159, v155
	v_rcp_f32_e32 v162, v149
	v_add_f32_e32 v149, 1.0, v151
	v_rcp_f32_e32 v161, v149
	v_add_f32_e32 v149, 1.0, v153
	v_rcp_f32_e32 v196, v197
	v_rcp_f32_e32 v198, v198
	v_rcp_f32_e32 v197, v200
	v_rcp_f32_e32 v163, v149
	v_pk_mul_f32 v[200:201], v[156:157], v[158:159]
	v_exp_f32_e32 v148, v148
	v_pk_mul_f32 v[200:201], v[200:201], v[200:201] op_sel:[0,1] op_sel_hi:[1,0]
	v_pk_mul_f32 v[202:203], v[196:197], v[198:199]
	v_mov_b32_e32 v149, v200
	v_mov_b32_e32 v151, v200
	v_pk_mul_f32 v[232:233], v[160:161], v[162:163]
	v_exp_f32_e32 v150, v150
	v_permlane32_swap_b32_e32 v149, v151
	v_mov_b32_e32 v234, v232
	v_mov_b32_e32 v235, v202
	v_mov_b32_e32 v202, v233
	v_pk_mul_f32 v[202:203], v[234:235], v[202:203]
	v_add_f32_e32 v148, 1.0, v148
	v_cndmask_b32_e64 v153, v149, v151, s[68:69]
	v_mov_b32_e32 v149, v203
	v_mov_b32_e32 v151, v203
	s_nop 1
	v_permlane32_swap_b32_e32 v149, v151
	v_mov_b32_e32 v155, v202
	v_mov_b32_e32 v201, v202
	v_add_f32_e32 v150, 1.0, v150
	s_nop 0
	v_permlane32_swap_b32_e32 v155, v201
	v_rcp_f32_e32 v148, v148
	v_rcp_f32_e32 v150, v150
	v_cndmask_b32_e64 v149, v149, v151, s[68:69]
	v_cndmask_b32_e64 v215, 1.0, v149, s[68:69]
	v_cndmask_b32_e64 v232, 1.0, v153, s[68:69]
	v_cndmask_b32_e64 v151, v155, v201, s[68:69]
	v_cndmask_b32_e64 v213, 1.0, v151, s[68:69]
	v_mul_f32_e32 v151, v202, v151
	v_mul_f32_e32 v155, v217, v151
	v_mul_f32_e32 v151, v203, v149
	v_mov_b32_e32 v149, v200
	v_pk_mul_f32 v[202:203], v[150:151], v[154:155]
	v_pk_mul_f32 v[200:201], v[148:149], v[152:153]
	v_mov_b32_e32 v233, v158
	v_pk_mul_f32 v[200:201], v[200:201], v[202:203]
	v_mul_f32_e32 v203, v232, v203
	v_mul_f32_e32 v202, v159, v203
	v_mov_b32_e32 v149, v200
	v_mov_b32_e32 v151, v200
	v_mul_f32_e32 v235, v157, v202
	s_nop 0
	v_permlane32_swap_b32_e32 v149, v151
	v_mul_f32_e32 v234, v158, v235
	v_mov_b32_e32 v158, v157
	v_mov_b32_e32 v232, v156
	v_pk_add_f32 v[156:157], v[158:159], 1.0 op_sel_hi:[1,0] neg_lo:[1,0] neg_hi:[1,0]
	v_mul_f32_e32 v159, v215, v155
	v_cndmask_b32_e64 v238, v149, v151, s[68:69]
	v_pk_add_f32 v[232:233], v[232:233], 1.0 op_sel_hi:[1,0] neg_lo:[1,0] neg_hi:[1,0]
	v_mul_f32_e32 v158, v199, v159
	v_cndmask_b32_e64 v149, 1.0, v238, s[68:69]
	v_pk_mul_f32 v[232:233], v[232:233], v[234:235]
	v_mul_f32_e32 v235, v197, v158
	v_pk_mul_f32 v[156:157], v[156:157], v[202:203]
	v_mov_b32_e32 v203, v198
	v_mul_f32_e32 v234, v198, v235
	v_mov_b32_e32 v198, v197
	v_mul_f32_e32 v155, v149, v201
	v_mov_b32_e32 v202, v196
	v_pk_add_f32 v[196:197], v[198:199], 1.0 op_sel_hi:[1,0] neg_lo:[1,0] neg_hi:[1,0]
	v_mov_b32_e32 v151, v154
	v_mul_f32_e32 v154, v154, v155
	v_pk_add_f32 v[202:203], v[202:203], 1.0 op_sel_hi:[1,0] neg_lo:[1,0] neg_hi:[1,0]
	v_pk_mul_f32 v[196:197], v[196:197], v[158:159]
	v_mov_b32_e32 v158, v160
	v_mov_b32_e32 v159, v162
	v_mov_b32_e32 v149, v152
	v_mul_f32_e32 v153, v150, v154
	v_pk_mul_f32 v[202:203], v[202:203], v[234:235]
	v_pk_add_f32 v[234:235], v[158:159], 1.0 op_sel_hi:[1,0] neg_lo:[1,0] neg_hi:[1,0]
	v_pk_add_f32 v[158:159], v[150:151], 1.0 op_sel_hi:[1,0] neg_lo:[1,0] neg_hi:[1,0]
	v_pk_add_f32 v[236:237], v[148:149], 1.0 op_sel_hi:[1,0] neg_lo:[1,0] neg_hi:[1,0]
	v_mul_f32_e32 v152, v152, v153
	v_pk_mul_f32 v[158:159], v[158:159], v[154:155]
	ds_read_b64_tr_b16 v[148:149], v209 offset:40960
	ds_read_b64_tr_b16 v[150:151], v209 offset:42112
	v_pk_mul_f32 v[152:153], v[236:237], v[152:153]
	v_cvt_pk_bf16_f32 v155, v156, v157
	v_cvt_pk_bf16_f32 v152, v152, v153
	v_cvt_pk_bf16_f32 v153, v158, v159
	ds_read_b64_tr_b16 v[158:159], v209 offset:42176
	ds_read_b64_tr_b16 v[156:157], v209 offset:41024
	v_mul_f32_e32 v199, v217, v213
	v_mul_f32_e32 v198, v163, v199
	v_cvt_pk_bf16_f32 v154, v232, v233
	s_waitcnt lgkmcnt(2)
	s_nop 0
	v_mfma_f32_32x32x16_bf16 v[132:147], v[148:151], v[152:155], v[132:147]
	v_mul_f32_e32 v149, v161, v198
	v_mul_f32_e32 v148, v162, v149
	v_mov_b32_e32 v162, v161
	v_add_f32_e64 v160, -v162, 1.0
	v_add_f32_e64 v161, -v163, 1.0
	v_pk_mul_f32 v[232:233], v[234:235], v[148:149]
	ds_read_b64_tr_b16 v[148:149], v209 offset:43264
	ds_read_b64_tr_b16 v[150:151], v209 offset:44416
	s_waitcnt lgkmcnt(2)
	v_mfma_f32_32x32x16_bf16 v[116:131], v[156:159], v[152:155], v[116:131]
	v_mul_f32_e64 v156, v160, v198
	v_mul_f32_e64 v157, v161, v199
	v_cvt_pk_bf16_f32 v152, v202, v203
	v_cvt_pk_bf16_f32 v155, v156, v157
	ds_read_b64_tr_b16 v[158:159], v209 offset:44480
	ds_read_b64_tr_b16 v[156:157], v209 offset:43328
	v_cvt_pk_bf16_f32 v153, v196, v197
	v_cvt_pk_bf16_f32 v154, v232, v233
	s_waitcnt lgkmcnt(2)
	s_nop 0
	v_mfma_f32_32x32x16_bf16 v[132:147], v[148:151], v[152:155], v[132:147]
	v_mul_f32_e32 v148, v200, v238
	v_mul_f32_e32 v217, v148, v201
	v_cmp_gt_f32_e32 vcc, s30, v217
	s_cmp_eq_u64 vcc, exec
	s_cselect_b64 s[12:13], -1, 0
	s_waitcnt lgkmcnt(0)
	v_mfma_f32_32x32x16_bf16 v[116:131], v[156:159], v[152:155], v[116:131]

; #define LAS __attribute__((address_space(3)))
; __device__ __forceinline__ float fast_rcp(float x) { return __builtin_amdgcn_rcpf(x); }
; __device__ __forceinline__ void sb_attn(Frame& F) {
;     ...
;             if (diag) {
; #pragma unroll
;                 for (int r = 0; r < 16; ++r) { const int key = (r & 3) + 8 * (r >> 2) + 4 * hi; s[r] = (key < r32) ? s[r] : -1e30f; }
;             }
;             float rm[16], bt[16];
; #pragma unroll
;             for (int r = 0; r < 16; ++r) {
;                 const float q1 = fast_rcp(1.0f + __builtin_amdgcn_exp2f(s[r]));
;                 rm[r] = q1;
;                 bt[r] = 1.0f - q1;
;             }
;             float Gs[4], Gp[4];
; #pragma unroll
;             for (int g4 = 0; g4 < 4; ++g4) { Gs[g4] = (rm[4 * g4] * rm[4 * g4 + 1]) * (rm[4 * g4 + 2] * rm[4 * g4 + 3]);
;                 const unsigned own = __builtin_bit_cast(unsigned, Gs[g4]);
;                 const u32x2 sw = __builtin_amdgcn_permlane32_swap(own, own, false, false);
;                 const unsigned r0 = sw.x, r1 = sw.y;
;                 Gp[g4] = __builtin_bit_cast(float, (r0 == own) ? r1 : r0); }
;             float run = C;
;             float a[16];
; #pragma unroll
;     ...
;                 float sfx = run * (hi == 0 ? Gp[g4] : 1.0f);
;                 a[4 * g4 + 3] = bt[4 * g4 + 3] * sfx; sfx *= rm[4 * g4 + 3];
;                 a[4 * g4 + 2] = bt[4 * g4 + 2] * sfx; sfx *= rm[4 * g4 + 2];
;                 a[4 * g4 + 1] = bt[4 * g4 + 1] * sfx; sfx *= rm[4 * g4 + 1];
;                 a[4 * g4 + 0] = bt[4 * g4 + 0] * sfx;
;                 run *= Gs[g4] * Gp[g4];
;             }
;             C = run;
; #pragma unroll
;             for (int s2 = 0; s2 < 2; ++s2) {
;                 u32x4 pw; pw.x = cvt_pk_bf16(a[8 * s2 + 0], a[8 * s2 + 1]); pw.y = cvt_pk_bf16(a[8 * s2 + 2], a[8 * s2 + 3]); pw.z = cvt_pk_bf16(a[8 * s2 + 4], a[8 * s2 + 5]); pw.w = cvt_pk_bf16(a[8 * s2 + 6], a[8 * s2 + 7]);
;                 const bf16x8 pf = __builtin_bit_cast(bf16x8, pw);
; #pragma unroll
;                 for (int dt = 0; dt < 2; ++dt) {
;                     const int dcol = 32 * dt + 16 * ((lane >> 4) & 1) + 4 * (lane & 3);
;                     const int krow = 16 * s2 + 4 * hi + ((lane & 15) >> 2);
;                     const s16x4 t0v = __builtin_bit_cast(s16x4, __builtin_amdgcn_ds_read_tr16_b64_v4i16((LAS s16x4*)(Vb + krow * P64 + dcol * 2)));
.LBB0_318:
	s_xor_b64 s[28:29], s[94:95], -1
	s_andn2_b64 vcc, exec, s[28:29]
	s_cbranch_vccnz .LBB0_311
	s_nop 3
	v_exp_f32_e32 v149, v101
	v_exp_f32_e32 v151, v104
	v_exp_f32_e32 v153, v115
	v_exp_f32_e32 v148, v100
	v_add_f32_e32 v149, 1.0, v149
	v_rcp_f32_e32 v152, v149
	v_exp_f32_e32 v149, v103
	v_add_f32_e32 v151, 1.0, v151
	v_rcp_f32_e32 v156, v151
	v_exp_f32_e32 v151, v106
	v_add_f32_e32 v149, 1.0, v149
	v_rcp_f32_e32 v154, v149
	v_exp_f32_e32 v149, v105
	v_add_f32_e32 v151, 1.0, v151
	v_rcp_f32_e32 v157, v151
	v_exp_f32_e32 v151, v108
	v_add_f32_e32 v149, 1.0, v149
	v_rcp_f32_e32 v158, v149
	v_exp_f32_e32 v149, v107
	v_add_f32_e32 v151, 1.0, v151
	v_rcp_f32_e32 v160, v151
	v_exp_f32_e32 v151, v110
	v_add_f32_e32 v149, 1.0, v149
	v_rcp_f32_e32 v159, v149
	v_exp_f32_e32 v149, v109
	v_add_f32_e32 v151, 1.0, v151
	v_rcp_f32_e32 v161, v151
	v_exp_f32_e32 v151, v112
	v_add_f32_e32 v149, 1.0, v149
	v_rcp_f32_e32 v162, v149
	v_exp_f32_e32 v149, v111
	v_add_f32_e32 v151, 1.0, v151
	v_rcp_f32_e32 v196, v151
	v_exp_f32_e32 v151, v114
	v_add_f32_e32 v149, 1.0, v149
	v_rcp_f32_e32 v163, v149
	v_exp_f32_e32 v149, v113
	v_pk_mul_f32 v[200:201], v[156:157], v[158:159]
	v_exp_f32_e32 v150, v102
	v_pk_mul_f32 v[200:201], v[200:201], v[200:201] op_sel:[0,1] op_sel_hi:[1,0]
	v_add_f32_e32 v149, 1.0, v149
	v_rcp_f32_e32 v198, v149
	v_add_f32_e32 v149, 1.0, v151
	v_rcp_f32_e32 v197, v149
	v_add_f32_e32 v149, 1.0, v153
	v_rcp_f32_e32 v199, v149
	v_mov_b32_e32 v149, v200
	v_mov_b32_e32 v151, v200
	v_pk_mul_f32 v[202:203], v[160:161], v[162:163]
	v_pk_mul_f32 v[232:233], v[196:197], v[198:199]
	v_permlane32_swap_b32_e32 v149, v151
	v_mov_b32_e32 v234, v232
	v_mov_b32_e32 v235, v202
	v_mov_b32_e32 v202, v233
	v_pk_mul_f32 v[202:203], v[234:235], v[202:203]
	v_add_f32_e32 v148, 1.0, v148
	v_cndmask_b32_e64 v153, v149, v151, s[68:69]
	v_mov_b32_e32 v149, v203
	v_mov_b32_e32 v151, v203
	s_nop 1
	v_permlane32_swap_b32_e32 v149, v151
	v_mov_b32_e32 v155, v202
	v_mov_b32_e32 v201, v202
	v_add_f32_e32 v150, 1.0, v150
	s_nop 0
	v_permlane32_swap_b32_e32 v155, v201
	v_rcp_f32_e32 v148, v148
	v_rcp_f32_e32 v150, v150
	v_cndmask_b32_e64 v149, v149, v151, s[68:69]
	v_cndmask_b32_e64 v215, 1.0, v149, s[68:69]
	v_cndmask_b32_e64 v232, 1.0, v153, s[68:69]
	v_cndmask_b32_e64 v151, v155, v201, s[68:69]
	v_cndmask_b32_e64 v213, 1.0, v151, s[68:69]
	v_mul_f32_e32 v151, v202, v151
	v_mul_f32_e32 v155, v231, v151
	v_mul_f32_e32 v151, v203, v149
	v_mov_b32_e32 v149, v200
	v_pk_mul_f32 v[202:203], v[150:151], v[154:155]
	v_pk_mul_f32 v[200:201], v[148:149], v[152:153]
	v_mov_b32_e32 v233, v158
	v_pk_mul_f32 v[200:201], v[200:201], v[202:203]
	v_mul_f32_e32 v203, v232, v203
	v_mul_f32_e32 v202, v159, v203
	v_mov_b32_e32 v149, v200
	v_mov_b32_e32 v151, v200
	v_mul_f32_e32 v235, v157, v202
	s_nop 0
	v_permlane32_swap_b32_e32 v149, v151
	v_mul_f32_e32 v234, v158, v235
	v_mov_b32_e32 v158, v157
	v_mov_b32_e32 v232, v156
	v_pk_add_f32 v[156:157], v[158:159], 1.0 op_sel_hi:[1,0] neg_lo:[1,0] neg_hi:[1,0]
	v_mul_f32_e32 v159, v215, v155
	v_cndmask_b32_e64 v238, v149, v151, s[68:69]
	v_pk_add_f32 v[232:233], v[232:233], 1.0 op_sel_hi:[1,0] neg_lo:[1,0] neg_hi:[1,0]
	v_mul_f32_e32 v158, v163, v159
	v_cndmask_b32_e64 v149, 1.0, v238, s[68:69]
	v_pk_mul_f32 v[232:233], v[232:233], v[234:235]
	v_mul_f32_e32 v235, v161, v158
	v_pk_mul_f32 v[156:157], v[156:157], v[202:203]
	v_mov_b32_e32 v203, v162
	v_mul_f32_e32 v234, v162, v235
	v_mov_b32_e32 v162, v161
	v_mul_f32_e32 v155, v149, v201
	v_mov_b32_e32 v202, v160
	v_pk_add_f32 v[160:161], v[162:163], 1.0 op_sel_hi:[1,0] neg_lo:[1,0] neg_hi:[1,0]
	v_mov_b32_e32 v151, v154
	v_mul_f32_e32 v154, v154, v155
	v_pk_add_f32 v[202:203], v[202:203], 1.0 op_sel_hi:[1,0] neg_lo:[1,0] neg_hi:[1,0]
	v_pk_mul_f32 v[160:161], v[160:161], v[158:159]
	v_mov_b32_e32 v158, v196
	v_mov_b32_e32 v159, v198
	v_mov_b32_e32 v149, v152
	v_mul_f32_e32 v153, v150, v154
	v_pk_mul_f32 v[202:203], v[202:203], v[234:235]
	v_pk_add_f32 v[234:235], v[158:159], 1.0 op_sel_hi:[1,0] neg_lo:[1,0] neg_hi:[1,0]
	v_pk_add_f32 v[158:159], v[150:151], 1.0 op_sel_hi:[1,0] neg_lo:[1,0] neg_hi:[1,0]
	v_pk_add_f32 v[236:237], v[148:149], 1.0 op_sel_hi:[1,0] neg_lo:[1,0] neg_hi:[1,0]
	v_mul_f32_e32 v152, v152, v153
	v_pk_mul_f32 v[158:159], v[158:159], v[154:155]
	ds_read_b64_tr_b16 v[148:149], v209 offset:40960
	ds_read_b64_tr_b16 v[150:151], v209 offset:42112
	v_pk_mul_f32 v[152:153], v[236:237], v[152:153]
	v_cvt_pk_bf16_f32 v155, v156, v157
	v_cvt_pk_bf16_f32 v152, v152, v153
	v_cvt_pk_bf16_f32 v153, v158, v159
	ds_read_b64_tr_b16 v[158:159], v209 offset:42176
	ds_read_b64_tr_b16 v[156:157], v209 offset:41024
	v_mul_f32_e32 v163, v231, v213
	v_mul_f32_e32 v162, v199, v163
	v_cvt_pk_bf16_f32 v154, v232, v233
	s_waitcnt lgkmcnt(2)
	s_nop 0
	v_mfma_f32_32x32x16_bf16 v[34:49], v[148:151], v[152:155], v[34:49]
	v_mul_f32_e32 v149, v197, v162
	v_mul_f32_e32 v148, v198, v149
	v_mov_b32_e32 v198, v197
	v_add_f32_e64 v196, -v198, 1.0
	v_add_f32_e64 v197, -v199, 1.0
	v_pk_mul_f32 v[232:233], v[234:235], v[148:149]
	ds_read_b64_tr_b16 v[148:149], v209 offset:43264
	ds_read_b64_tr_b16 v[150:151], v209 offset:44416
	s_waitcnt lgkmcnt(2)
	v_mfma_f32_32x32x16_bf16 v[50:65], v[156:159], v[152:155], v[50:65]
	v_mul_f32_e64 v156, v196, v162
	v_mul_f32_e64 v157, v197, v163
	v_cvt_pk_bf16_f32 v152, v202, v203
	v_cvt_pk_bf16_f32 v155, v156, v157
	ds_read_b64_tr_b16 v[158:159], v209 offset:44480
	ds_read_b64_tr_b16 v[156:157], v209 offset:43328
	v_cvt_pk_bf16_f32 v153, v160, v161
	v_cvt_pk_bf16_f32 v154, v232, v233
	s_waitcnt lgkmcnt(2)
	s_nop 0
	v_mfma_f32_32x32x16_bf16 v[34:49], v[148:151], v[152:155], v[34:49]
	v_mul_f32_e32 v148, v200, v238
	v_mul_f32_e32 v231, v148, v201
	v_cmp_gt_f32_e32 vcc, s30, v231
	s_cmp_eq_u64 vcc, exec
	s_cselect_b64 s[72:73], -1, 0
	s_waitcnt lgkmcnt(0)
	v_mfma_f32_32x32x16_bf16 v[50:65], v[156:159], v[152:155], v[50:65]
	s_branch .LBB0_311
